# grid barrier: non-leader blocks poll TOPGEN directly instead of the per-XCD release word
# speedup vs baseline: 1.0076x; 1.0003x over previous
; DI unsigned xb_ld(unsigned* p)              { return __hip_atomic_load(p, __ATOMIC_RELAXED, __HIP_MEMORY_SCOPE_AGENT); }
; DI unsigned xb_add(unsigned* p, unsigned v) { return __hip_atomic_fetch_add(p, v, __ATOMIC_RELAXED, __HIP_MEMORY_SCOPE_AGENT); }
; #define XB_SPIN(cond, bar) do { unsigned _sp = 0; while (cond) { __builtin_amdgcn_s_sleep(1); \
;     if ((++_sp & 255u) == 0u) { if (xb_ld(&(bar)[XB_TMO])) break; if (_sp > XB_SPIN_CAP) { atomicAdd(&(bar)[XB_TMO], 1u); break; } } } } while (0)
; DI void xcd_barrier(const XcdBarrier& b) {
;     ...
;     const unsigned old = xb_add(&bar[XB_XSUB(b.x)], 1u);
;     const unsigned gen = old / nloc;
;     if (old + 1u == (gen + 1u) * nloc) {
;       __builtin_amdgcn_fence(__ATOMIC_RELEASE, "agent");
;       asm volatile("s_waitcnt vmcnt(0)" ::: "memory");
;       const unsigned og = xb_add(&bar[XB_TOP], 1u);
;       const unsigned tg = og / nx;
;       if (og + 1u == (tg + 1u) * nx) xb_add(&bar[XB_TOPGEN], 1u);
;       else XB_SPIN(xb_ld(&bar[XB_TOPGEN]) == tg, bar);
;       __builtin_amdgcn_fence(__ATOMIC_ACQUIRE, "agent");
;       xb_add(&bar[XB_XGEN(b.x)], 1u);
;       asm volatile("s_waitcnt vmcnt(0)" ::: "memory");
;     } else {
;       XB_SPIN(xb_ld(&bar[XB_XGEN(b.x)]) == gen, bar);
.LBB0_2080:
	s_or_b64 exec, exec, s[30:31]
	v_cvt_f32_u32_e32 v5, v3
	s_waitcnt vmcnt(0)
	v_readfirstlane_b32 s28, v4
	v_sub_u32_e32 v4, 0, v3
	v_rcp_iflag_f32_e32 v5, v5
	v_add_u32_e32 v6, s28, v0
	v_mul_f32_e32 v5, 0x4f7ffffe, v5
	v_cvt_u32_f32_e32 v5, v5
	v_mul_lo_u32 v0, v4, v5
	v_mul_hi_u32 v0, v5, v0
	v_add_u32_e32 v0, v5, v0
	v_mul_hi_u32 v0, v6, v0
	v_mul_lo_u32 v4, v0, v3
	v_sub_u32_e32 v4, v6, v4
	v_add_u32_e32 v5, 1, v0
	v_cmp_ge_u32_e32 vcc, v4, v3
	s_nop 1
	v_cndmask_b32_e32 v0, v0, v5, vcc
	v_sub_u32_e32 v5, v4, v3
	v_cndmask_b32_e32 v4, v4, v5, vcc
	v_add_u32_e32 v5, 1, v0
	v_cmp_ge_u32_e32 vcc, v4, v3
	v_add_u32_e32 v4, 1, v6
	s_nop 0
	v_cndmask_b32_e32 v0, v0, v5, vcc
	v_mul_lo_u32 v5, v3, v0
	v_add_u32_e32 v3, v5, v3
	v_cmp_ne_u32_e32 vcc, v4, v3
	s_and_saveexec_b64 s[30:31], vcc
	s_xor_b64 s[30:31], exec, s[30:31]
	s_cbranch_execz .LBB0_2094
	v_readlane_b32 s4, v254, 62
	v_readlane_b32 s5, v254, 63
	s_waitcnt lgkmcnt(0)
	s_nop 3
	global_load_dword v2, v1, s[4:5] sc1
	s_waitcnt vmcnt(0)
	v_cmp_eq_u32_e32 vcc, v2, v0
	s_and_saveexec_b64 s[40:41], vcc
	s_cbranch_execz .LBB0_2093
	s_mov_b32 s28, 1
	s_mov_b64 s[42:43], 0
	s_branch .LBB0_2084
